# v4 + P4 epilogue relu folded to one v_max per element (128 fewer VALU per tile), store-data wait states kept
# baseline (speedup 1.0000x reference)
; #define PG8_STAGE(bufoff, gbase, voff) do { _Pragma("unroll") for (int _i = 0; _i < 2; ++_i) \
;         __builtin_amdgcn_global_load_lds((const unsigned*)((const char*)(gbase) + (voff)[_i]), (LAS unsigned*)(lds + (bufoff) + ldsw + _i * 8192), 16, 0, 0); } while (0)
; #define PG8_LDA(dst, b, h) do { _Pragma("unroll") for (int m = 0; m < 4; ++m) _Pragma("unroll") for (int k = 0; k < 2; ++k) dst[m][k] = *(const LAS bf16x8*)(lds + PG8_SA(b, h) + aoff + m * 2048 + k * 1024); } while (0)
; #define PG8_LDB(dst, b, h) do { _Pragma("unroll") for (int n = 0; n < 2; ++n) _Pragma("unroll") for (int k = 0; k < 2; ++k) dst[n][k] = *(const LAS bf16x8*)(lds + PG8_SB(b, h) + boff + n * 2048 + k * 1024); } while (0)
; #define PG8_MMA(ai, bj, At, Bt) do { __builtin_amdgcn_s_setprio(1); _Pragma("unroll") for (int m = 0; m < 4; ++m) _Pragma("unroll") for (int n = 0; n < 2; ++n) _Pragma("unroll") for (int k = 0; k < 2; ++k) \
;         acc[ai][bj][m][n] = __builtin_amdgcn_mfma_f32_16x16x32_bf16(Bt[n][k], At[m][k], acc[ai][bj][m][n], 0, 0, 0); __builtin_amdgcn_s_setprio(0); } while (0)
; #define PG8_WAIT_V(n) asm volatile("s_waitcnt vmcnt(" #n ")" ::: "memory")
; #define PG8_WAIT_L(n) asm volatile("s_waitcnt lgkmcnt(" #n ")" ::: "memory")
; #define PG8_BAR __builtin_amdgcn_s_barrier()
; #define PG8_SCHED __builtin_amdgcn_sched_barrier(0)
; template <class Epi, class Ptrs>
; __device__ __forceinline__ void gemm_phase(LAS unsigned char* lds, const int K, const StaticOrder& S, const Ptrs& P, const Epi& E) {
;     ...
;             PG8_LDB(B0, 0, 0); PG8_SCHED; PG8_LDA(At, 0, 0); PG8_STAGE(PG8_SA(1, 1), a1 + hstep, voffA);
;             PG8_WAIT_L(8); PG8_BAR; PG8_WAIT_L(0); PG8_MMA(0, 0, At, B0); PG8_BAR; PG8_SCHED;
;             PG8_LDB(B1, 0, 1); PG8_STAGE(PG8_SB(0, 0), b2, voffB);
;             PG8_BAR; PG8_WAIT_L(0); PG8_MMA(0, 1, At, B1); PG8_BAR;
;             PG8_LDA(At, 0, 1); PG8_STAGE(PG8_SA(0, 0), a2, voffA);
;             PG8_BAR; PG8_WAIT_L(0); PG8_MMA(1, 0, At, B0); PG8_BAR; PG8_SCHED;
;             PG8_STAGE(PG8_SB(0, 1), b2 + hstep, voffB);
;             PG8_WAIT_V(6); PG8_BAR; PG8_MMA(1, 1, At, B1); PG8_BAR;
;             PG8_LDB(B0, 1, 0); PG8_SCHED; PG8_LDA(At, 1, 0); PG8_STAGE(PG8_SA(0, 1), a2 + hstep, voffA);
;             PG8_WAIT_L(8); PG8_BAR; PG8_WAIT_L(0); PG8_MMA(0, 0, At, B0); PG8_BAR; PG8_SCHED;
.LBB0_433:
	ds_read_b128 v[152:155], v149
	ds_read_b128 v[156:159], v149 offset:1024
	ds_read_b128 v[160:163], v149 offset:2048
	ds_read_b128 v[164:167], v149 offset:3072
	s_add_u32 s42, s40, 0xfffc0080
	s_addc_u32 s43, s41, -1
	s_cmp_eq_u32 s70, 12
	s_cselect_b32 s45, s1, s43
	s_cselect_b32 s44, s0, s42
	s_cselect_b32 s43, s37, s25
	s_cselect_b32 s42, s36, s23
	v_lshl_add_u64 v[144:145], s[40:41], 0, v[136:137]
	s_add_i32 m0, s39, 0xc000
	ds_read_b128 v[168:171], v150
	ds_read_b128 v[172:175], v150 offset:1024
	ds_read_b128 v[176:179], v150 offset:2048
	ds_read_b128 v[180:183], v150 offset:3072
	ds_read_b128 v[184:187], v150 offset:4096
	ds_read_b128 v[188:191], v150 offset:5120
	ds_read_b128 v[192:195], v150 offset:6144
	ds_read_b128 v[196:199], v150 offset:7168
	global_load_lds_dwordx4 v[144:145], off
	v_lshl_add_u64 v[144:145], s[40:41], 0, v[138:139]
	s_add_i32 m0, s39, 0xe000
	s_nop 0
	global_load_lds_dwordx4 v[144:145], off
	s_waitcnt lgkmcnt(8)
	s_barrier
	s_waitcnt lgkmcnt(0)
	s_setprio 1
	s_waitcnt lgkmcnt(0)
	v_mfma_f32_16x16x32_bf16 v[124:127], v[152:155], v[168:171], v[124:127]
	v_mfma_f32_16x16x32_bf16 v[124:127], v[156:159], v[172:175], v[124:127]
	v_mfma_f32_16x16x32_bf16 v[120:123], v[164:167], v[172:175], v[120:123]
	v_mfma_f32_16x16x32_bf16 v[120:123], v[160:163], v[168:171], v[120:123]
	v_mfma_f32_16x16x32_bf16 v[104:107], v[160:163], v[176:179], v[104:107]
	v_mfma_f32_16x16x32_bf16 v[104:107], v[164:167], v[180:183], v[104:107]
	v_mfma_f32_16x16x32_bf16 v[108:111], v[156:159], v[180:183], v[108:111]
	v_mfma_f32_16x16x32_bf16 v[108:111], v[152:155], v[176:179], v[108:111]
	v_mfma_f32_16x16x32_bf16 v[92:95], v[152:155], v[184:187], v[92:95]
	v_mfma_f32_16x16x32_bf16 v[92:95], v[156:159], v[188:191], v[92:95]
	v_mfma_f32_16x16x32_bf16 v[88:91], v[164:167], v[188:191], v[88:91]
	v_mfma_f32_16x16x32_bf16 v[88:91], v[160:163], v[184:187], v[88:91]
	v_mfma_f32_16x16x32_bf16 v[72:75], v[160:163], v[192:195], v[72:75]
	v_mfma_f32_16x16x32_bf16 v[72:75], v[164:167], v[196:199], v[72:75]
	v_mfma_f32_16x16x32_bf16 v[76:79], v[156:159], v[196:199], v[76:79]
	v_mfma_f32_16x16x32_bf16 v[76:79], v[152:155], v[192:195], v[76:79]
	s_setprio 0
	s_barrier
	s_add_i32 s71, s63, s51
	v_lshl_add_u64 v[144:145], s[42:43], 0, v[130:131]
	s_mov_b32 m0, s71
	ds_read_b128 v[200:203], v151
	ds_read_b128 v[204:207], v151 offset:1024
	ds_read_b128 v[210:213], v151 offset:2048
	ds_read_b128 v[214:217], v151 offset:3072
	global_load_lds_dwordx4 v[144:145], off
	v_lshl_add_u64 v[218:219], s[42:43], 0, v[134:135]
	s_add_i32 m0, s71, 0x2000
	s_nop 0
	global_load_lds_dwordx4 v[218:219], off
	s_barrier
	s_waitcnt lgkmcnt(0)
	s_setprio 1
	s_waitcnt lgkmcnt(0)
	v_mfma_f32_16x16x32_bf16 v[116:119], v[200:203], v[168:171], v[116:119]
	v_mfma_f32_16x16x32_bf16 v[116:119], v[204:207], v[172:175], v[116:119]
	v_mfma_f32_16x16x32_bf16 v[112:115], v[214:217], v[172:175], v[112:115]
	v_mfma_f32_16x16x32_bf16 v[112:115], v[210:213], v[168:171], v[112:115]
	v_mfma_f32_16x16x32_bf16 v[96:99], v[210:213], v[176:179], v[96:99]
	v_mfma_f32_16x16x32_bf16 v[96:99], v[214:217], v[180:183], v[96:99]
	v_mfma_f32_16x16x32_bf16 v[100:103], v[204:207], v[180:183], v[100:103]
	v_mfma_f32_16x16x32_bf16 v[100:103], v[200:203], v[176:179], v[100:103]
	v_mfma_f32_16x16x32_bf16 v[84:87], v[200:203], v[184:187], v[84:87]
	v_mfma_f32_16x16x32_bf16 v[84:87], v[204:207], v[188:191], v[84:87]
	v_mfma_f32_16x16x32_bf16 v[80:83], v[214:217], v[188:191], v[80:83]
	v_mfma_f32_16x16x32_bf16 v[80:83], v[210:213], v[184:187], v[80:83]
	v_mfma_f32_16x16x32_bf16 v[64:67], v[210:213], v[192:195], v[64:67]
	v_mfma_f32_16x16x32_bf16 v[64:67], v[214:217], v[196:199], v[64:67]
	v_mfma_f32_16x16x32_bf16 v[68:71], v[204:207], v[196:199], v[68:71]
	v_mfma_f32_16x16x32_bf16 v[68:71], v[200:203], v[192:195], v[68:71]
	s_setprio 0
	s_mov_b32 m0, s39
	v_lshl_add_u64 v[220:221], s[44:45], 0, v[128:129]
	s_barrier
	ds_read_b128 v[168:171], v150 offset:16384
	ds_read_b128 v[172:175], v150 offset:17408
	ds_read_b128 v[176:179], v150 offset:18432
	ds_read_b128 v[180:183], v150 offset:19456
	ds_read_b128 v[184:187], v150 offset:20480
	ds_read_b128 v[188:191], v150 offset:21504
	ds_read_b128 v[192:195], v150 offset:22528
	ds_read_b128 v[196:199], v150 offset:23552
	global_load_lds_dwordx4 v[220:221], off
	v_lshl_add_u64 v[222:223], s[44:45], 0, v[132:133]
	s_mov_b32 m0, s56
	s_nop 0
	global_load_lds_dwordx4 v[222:223], off
	s_barrier
	s_waitcnt lgkmcnt(0)
	s_setprio 1
	s_waitcnt lgkmcnt(0)
	v_mfma_f32_16x16x32_bf16 v[60:63], v[152:155], v[168:171], v[60:63]
	v_mfma_f32_16x16x32_bf16 v[60:63], v[156:159], v[172:175], v[60:63]
	v_mfma_f32_16x16x32_bf16 v[56:59], v[164:167], v[172:175], v[56:59]
	v_mfma_f32_16x16x32_bf16 v[56:59], v[160:163], v[168:171], v[56:59]
	v_mfma_f32_16x16x32_bf16 v[40:43], v[160:163], v[176:179], v[40:43]
	v_mfma_f32_16x16x32_bf16 v[40:43], v[164:167], v[180:183], v[40:43]
	v_mfma_f32_16x16x32_bf16 v[44:47], v[156:159], v[180:183], v[44:47]
	v_mfma_f32_16x16x32_bf16 v[44:47], v[152:155], v[176:179], v[44:47]
	v_mfma_f32_16x16x32_bf16 v[28:31], v[152:155], v[184:187], v[28:31]
	v_mfma_f32_16x16x32_bf16 v[28:31], v[156:159], v[188:191], v[28:31]
	v_mfma_f32_16x16x32_bf16 v[24:27], v[164:167], v[188:191], v[24:27]
	v_mfma_f32_16x16x32_bf16 v[24:27], v[160:163], v[184:187], v[24:27]
	v_mfma_f32_16x16x32_bf16 v[8:11], v[160:163], v[192:195], v[8:11]
	v_mfma_f32_16x16x32_bf16 v[8:11], v[164:167], v[196:199], v[8:11]
	v_mfma_f32_16x16x32_bf16 v[12:15], v[156:159], v[196:199], v[12:15]
	v_mfma_f32_16x16x32_bf16 v[12:15], v[152:155], v[192:195], v[12:15]
	s_setprio 0
	s_barrier
; #define PG8_STAGE(bufoff, gbase, voff) do { _Pragma("unroll") for (int _i = 0; _i < 2; ++_i) \
;         __builtin_amdgcn_global_load_lds((const unsigned*)((const char*)(gbase) + (voff)[_i]), (LAS unsigned*)(lds + (bufoff) + ldsw + _i * 8192), 16, 0, 0); } while (0)
; #define PG8_LDA(dst, b, h) do { _Pragma("unroll") for (int m = 0; m < 4; ++m) _Pragma("unroll") for (int k = 0; k < 2; ++k) dst[m][k] = *(const LAS bf16x8*)(lds + PG8_SA(b, h) + aoff + m * 2048 + k * 1024); } while (0)
; #define PG8_LDB(dst, b, h) do { _Pragma("unroll") for (int n = 0; n < 2; ++n) _Pragma("unroll") for (int k = 0; k < 2; ++k) dst[n][k] = *(const LAS bf16x8*)(lds + PG8_SB(b, h) + boff + n * 2048 + k * 1024); } while (0)
; #define PG8_MMA(ai, bj, At, Bt) do { __builtin_amdgcn_s_setprio(1); _Pragma("unroll") for (int m = 0; m < 4; ++m) _Pragma("unroll") for (int n = 0; n < 2; ++n) _Pragma("unroll") for (int k = 0; k < 2; ++k) \
;         acc[ai][bj][m][n] = __builtin_amdgcn_mfma_f32_16x16x32_bf16(Bt[n][k], At[m][k], acc[ai][bj][m][n], 0, 0, 0); __builtin_amdgcn_s_setprio(0); } while (0)
; #define PG8_WAIT_V(n) asm volatile("s_waitcnt vmcnt(" #n ")" ::: "memory")
; #define PG8_WAIT_L(n) asm volatile("s_waitcnt lgkmcnt(" #n ")" ::: "memory")
; #define PG8_BAR __builtin_amdgcn_s_barrier()
; #define PG8_SCHED __builtin_amdgcn_sched_barrier(0)
; template <class Epi, class Ptrs>
; __device__ __forceinline__ void gemm_phase(LAS unsigned char* lds, const int K, const StaticOrder& S, const Ptrs& P, const Epi& E) {
;     ...
;             PG8_WAIT_V(6); PG8_BAR; PG8_MMA(1, 1, At, B1); PG8_BAR;
;             PG8_LDB(B0, 1, 0); PG8_SCHED; PG8_LDA(At, 1, 0); PG8_STAGE(PG8_SA(0, 1), a2 + hstep, voffA);
;             PG8_WAIT_L(8); PG8_BAR; PG8_WAIT_L(0); PG8_MMA(0, 0, At, B0); PG8_BAR; PG8_SCHED;
;             PG8_LDB(B1, 1, 1); PG8_STAGE(PG8_SB(1, 0), b3, voffB);
;             PG8_BAR; PG8_WAIT_L(0); PG8_MMA(0, 1, At, B1); PG8_BAR;
;             PG8_LDA(At, 1, 1); PG8_STAGE(PG8_SA(1, 0), a3, voffA);
;             PG8_BAR; PG8_WAIT_L(0); PG8_MMA(1, 0, At, B0); PG8_BAR; PG8_SCHED;
	s_add_u32 s72, s42, 0x40000
	s_addc_u32 s73, s43, 0
	s_add_i32 s71, s64, s51
	v_lshl_add_u64 v[152:153], s[72:73], 0, v[130:131]
	s_mov_b32 m0, s71
	s_nop 0
	global_load_lds_dwordx4 v[152:153], off
	v_lshl_add_u64 v[152:153], s[72:73], 0, v[134:135]
	s_add_i32 m0, s71, 0x2000
	s_nop 0
	global_load_lds_dwordx4 v[152:153], off
	s_waitcnt vmcnt(6)
	s_barrier
	s_setprio 1
	v_mfma_f32_16x16x32_bf16 v[52:55], v[200:203], v[168:171], v[52:55]
	v_mfma_f32_16x16x32_bf16 v[52:55], v[204:207], v[172:175], v[52:55]
	v_mfma_f32_16x16x32_bf16 v[48:51], v[214:217], v[172:175], v[48:51]
	v_mfma_f32_16x16x32_bf16 v[48:51], v[210:213], v[168:171], v[48:51]
	v_mfma_f32_16x16x32_bf16 v[32:35], v[210:213], v[176:179], v[32:35]
	v_mfma_f32_16x16x32_bf16 v[32:35], v[214:217], v[180:183], v[32:35]
	v_mfma_f32_16x16x32_bf16 v[36:39], v[204:207], v[180:183], v[36:39]
	v_mfma_f32_16x16x32_bf16 v[36:39], v[200:203], v[176:179], v[36:39]
	v_mfma_f32_16x16x32_bf16 v[20:23], v[200:203], v[184:187], v[20:23]
	v_mfma_f32_16x16x32_bf16 v[20:23], v[204:207], v[188:191], v[20:23]
	v_mfma_f32_16x16x32_bf16 v[16:19], v[214:217], v[188:191], v[16:19]
	v_mfma_f32_16x16x32_bf16 v[16:19], v[210:213], v[184:187], v[16:19]
	v_mfma_f32_16x16x32_bf16 v[0:3], v[210:213], v[192:195], v[0:3]
	v_mfma_f32_16x16x32_bf16 v[0:3], v[214:217], v[196:199], v[0:3]
	v_mfma_f32_16x16x32_bf16 v[4:7], v[204:207], v[196:199], v[4:7]
	v_mfma_f32_16x16x32_bf16 v[4:7], v[200:203], v[192:195], v[4:7]
	s_setprio 0
	s_add_i32 s71, 0, 0x18000
	v_add_u32_e32 v164, s71, v147
	s_barrier
	ds_read_b128 v[152:155], v164
	ds_read_b128 v[156:159], v164 offset:1024
	ds_read_b128 v[160:163], v164 offset:2048
	ds_read_b128 v[164:167], v164 offset:3072
	s_add_u32 s44, s44, 0x40000
	s_addc_u32 s45, s45, 0
	s_mov_b32 m0, s57
	v_lshl_add_u64 v[200:201], s[44:45], 0, v[128:129]
	ds_read_b128 v[168:171], v150 offset:32768
	ds_read_b128 v[172:175], v150 offset:33792
	ds_read_b128 v[176:179], v150 offset:34816
	ds_read_b128 v[180:183], v150 offset:35840
	ds_read_b128 v[184:187], v150 offset:36864
	ds_read_b128 v[188:191], v150 offset:37888
	ds_read_b128 v[192:195], v150 offset:38912
	ds_read_b128 v[196:199], v150 offset:39936
	global_load_lds_dwordx4 v[200:201], off
	v_lshl_add_u64 v[200:201], s[44:45], 0, v[132:133]
	s_mov_b32 m0, s58
	s_nop 0
	global_load_lds_dwordx4 v[200:201], off
	s_waitcnt lgkmcnt(8)
	s_barrier
	s_waitcnt lgkmcnt(0)
	s_setprio 1
	s_waitcnt lgkmcnt(0)
	v_mfma_f32_16x16x32_bf16 v[124:127], v[152:155], v[168:171], v[124:127]
	v_mfma_f32_16x16x32_bf16 v[124:127], v[156:159], v[172:175], v[124:127]
	v_mfma_f32_16x16x32_bf16 v[120:123], v[164:167], v[172:175], v[120:123]
	v_mfma_f32_16x16x32_bf16 v[120:123], v[160:163], v[168:171], v[120:123]
	v_mfma_f32_16x16x32_bf16 v[104:107], v[160:163], v[176:179], v[104:107]
	v_mfma_f32_16x16x32_bf16 v[104:107], v[164:167], v[180:183], v[104:107]
	v_mfma_f32_16x16x32_bf16 v[108:111], v[156:159], v[180:183], v[108:111]
	v_mfma_f32_16x16x32_bf16 v[108:111], v[152:155], v[176:179], v[108:111]
	v_mfma_f32_16x16x32_bf16 v[92:95], v[152:155], v[184:187], v[92:95]
	v_mfma_f32_16x16x32_bf16 v[92:95], v[156:159], v[188:191], v[92:95]
	v_mfma_f32_16x16x32_bf16 v[88:91], v[164:167], v[188:191], v[88:91]
	v_mfma_f32_16x16x32_bf16 v[88:91], v[160:163], v[184:187], v[88:91]
	v_mfma_f32_16x16x32_bf16 v[72:75], v[160:163], v[192:195], v[72:75]
	v_mfma_f32_16x16x32_bf16 v[72:75], v[164:167], v[196:199], v[72:75]
	v_mfma_f32_16x16x32_bf16 v[76:79], v[156:159], v[196:199], v[76:79]
	v_mfma_f32_16x16x32_bf16 v[76:79], v[152:155], v[192:195], v[76:79]
	s_setprio 0
	s_barrier
	s_add_i32 s44, 0, 0x1c000
	s_add_i32 s45, s71, s51
	v_add_u32_e32 v209, s44, v147
	v_lshl_add_u64 v[144:145], v[144:145], 0, s[12:13]
	s_mov_b32 m0, s45
	ds_read_b128 v[200:203], v209
	ds_read_b128 v[204:207], v209 offset:1024
	ds_read_b128 v[210:213], v209 offset:2048
	ds_read_b128 v[214:217], v209 offset:3072
	global_load_lds_dwordx4 v[144:145], off
	v_lshl_add_u64 v[144:145], v[218:219], 0, s[12:13]
	s_add_i32 m0, s45, 0x2000
	s_nop 0
	global_load_lds_dwordx4 v[144:145], off
	s_barrier
	s_waitcnt lgkmcnt(0)
	s_setprio 1
	s_waitcnt lgkmcnt(0)
	v_mfma_f32_16x16x32_bf16 v[116:119], v[200:203], v[168:171], v[116:119]
	v_mfma_f32_16x16x32_bf16 v[116:119], v[204:207], v[172:175], v[116:119]
	v_mfma_f32_16x16x32_bf16 v[112:115], v[214:217], v[172:175], v[112:115]
	v_mfma_f32_16x16x32_bf16 v[112:115], v[210:213], v[168:171], v[112:115]
	v_mfma_f32_16x16x32_bf16 v[96:99], v[210:213], v[176:179], v[96:99]
	v_mfma_f32_16x16x32_bf16 v[96:99], v[214:217], v[180:183], v[96:99]
	v_mfma_f32_16x16x32_bf16 v[100:103], v[204:207], v[180:183], v[100:103]
	v_mfma_f32_16x16x32_bf16 v[100:103], v[200:203], v[176:179], v[100:103]
	v_mfma_f32_16x16x32_bf16 v[84:87], v[200:203], v[184:187], v[84:87]
	v_mfma_f32_16x16x32_bf16 v[84:87], v[204:207], v[188:191], v[84:87]
	v_mfma_f32_16x16x32_bf16 v[80:83], v[214:217], v[188:191], v[80:83]
	v_mfma_f32_16x16x32_bf16 v[80:83], v[210:213], v[184:187], v[80:83]
	v_mfma_f32_16x16x32_bf16 v[64:67], v[210:213], v[192:195], v[64:67]
	v_mfma_f32_16x16x32_bf16 v[64:67], v[214:217], v[196:199], v[64:67]
	v_mfma_f32_16x16x32_bf16 v[68:71], v[204:207], v[196:199], v[68:71]
	v_mfma_f32_16x16x32_bf16 v[68:71], v[200:203], v[192:195], v[68:71]
	s_setprio 0
	s_mov_b32 m0, s61
	v_lshl_add_u64 v[144:145], v[220:221], 0, s[12:13]
	s_barrier
	ds_read_b128 v[168:171], v150 offset:49152
	ds_read_b128 v[172:175], v150 offset:50176
	ds_read_b128 v[176:179], v150 offset:51200
	ds_read_b128 v[180:183], v150 offset:52224
	ds_read_b128 v[184:187], v150 offset:53248
	ds_read_b128 v[188:191], v150 offset:54272
	ds_read_b128 v[192:195], v150 offset:55296
	ds_read_b128 v[196:199], v150 offset:56320
	global_load_lds_dwordx4 v[144:145], off
	v_lshl_add_u64 v[144:145], v[222:223], 0, s[12:13]
	s_mov_b32 m0, s62
	s_nop 0
	global_load_lds_dwordx4 v[144:145], off
	s_barrier
; __device__ __forceinline__ unsigned cvt_pk_bf16(float lo, float hi) { unsigned r; asm volatile("v_cvt_pk_bf16_f32 %0, %1, %2" : "=v"(r) : "v"(lo), "v"(hi)); return r; }
; #define PG8_STAGE(bufoff, gbase, voff) do { _Pragma("unroll") for (int _i = 0; _i < 2; ++_i) \
;         __builtin_amdgcn_global_load_lds((const unsigned*)((const char*)(gbase) + (voff)[_i]), (LAS unsigned*)(lds + (bufoff) + ldsw + _i * 8192), 16, 0, 0); } while (0)
; #define PG8_MMA(ai, bj, At, Bt) do { __builtin_amdgcn_s_setprio(1); _Pragma("unroll") for (int m = 0; m < 4; ++m) _Pragma("unroll") for (int n = 0; n < 2; ++n) _Pragma("unroll") for (int k = 0; k < 2; ++k) \
;         acc[ai][bj][m][n] = __builtin_amdgcn_mfma_f32_16x16x32_bf16(Bt[n][k], At[m][k], acc[ai][bj][m][n], 0, 0, 0); __builtin_amdgcn_s_setprio(0); } while (0)
; #define PG8_WAIT_V(n) asm volatile("s_waitcnt vmcnt(" #n ")" ::: "memory")
; #define PG8_WAIT_L(n) asm volatile("s_waitcnt lgkmcnt(" #n ")" ::: "memory")
; #define PG8_BAR __builtin_amdgcn_s_barrier()
; #define PG8_SCHED __builtin_amdgcn_sched_barrier(0)
; template <class Epi, class Ptrs>
; __device__ __forceinline__ void gemm_phase(LAS unsigned char* lds, const int K, const StaticOrder& S, const Ptrs& P, const Epi& E) {
;     ...
;             PG8_BAR; PG8_WAIT_L(0); PG8_MMA(1, 0, At, B0); PG8_BAR; PG8_SCHED;
;             PG8_STAGE(PG8_SB(1, 1), b3 + hstep, voffB);
;             PG8_WAIT_V(6); PG8_BAR; PG8_MMA(1, 1, At, B1); PG8_BAR;
;         }
;     __device__ __forceinline__ void operator()(const f32x4 (&acc)[2][2][4][2], const Unit& u, int ui, int wr, int wc, int fr, int fq) const {
;         const int row0 = u.pm * 256 + wr * 64 + fr, col0 = u.pn * 256 + wc * 32 + 8 * fq;
; #pragma unroll
;         for (int ai = 0; ai < 2; ++ai)
; #pragma unroll
;             for (int m = 0; m < 4; ++m) { bf16_t* rowp = hid + (size_t)(row0 + ai * 128 + m * 16) * DFF + col0;
; #pragma unroll
;                 for (int bj = 0; bj < 2; ++bj) { f32x4 v0 = acc[ai][bj][m][0], v1 = acc[ai][bj][m][1];
; #pragma unroll
;                     for (int j = 0; j < 4; ++j) { const float a = fmaxf(v0[j], 0.f), b = fmaxf(v1[j], 0.f); v0[j] = a * a; v1[j] = b * b; }
;                     u32x4 w; w.x = cvt_pk_bf16(v0[0], v0[1]); w.y = cvt_pk_bf16(v0[2], v0[3]); w.z = cvt_pk_bf16(v1[0], v1[1]); w.w = cvt_pk_bf16(v1[2], v1[3]);
;                     *(u32x4*)(rowp + bj * 128) = w; } }
	s_waitcnt lgkmcnt(0)
	s_setprio 1
	s_waitcnt lgkmcnt(0)
	v_mfma_f32_16x16x32_bf16 v[60:63], v[152:155], v[168:171], v[60:63]
	v_mfma_f32_16x16x32_bf16 v[60:63], v[156:159], v[172:175], v[60:63]
	v_mfma_f32_16x16x32_bf16 v[56:59], v[164:167], v[172:175], v[56:59]
	v_mfma_f32_16x16x32_bf16 v[56:59], v[160:163], v[168:171], v[56:59]
	v_mfma_f32_16x16x32_bf16 v[40:43], v[160:163], v[176:179], v[40:43]
	v_mfma_f32_16x16x32_bf16 v[40:43], v[164:167], v[180:183], v[40:43]
	v_mfma_f32_16x16x32_bf16 v[44:47], v[156:159], v[180:183], v[44:47]
	v_mfma_f32_16x16x32_bf16 v[44:47], v[152:155], v[176:179], v[44:47]
	v_mfma_f32_16x16x32_bf16 v[28:31], v[152:155], v[184:187], v[28:31]
	v_mfma_f32_16x16x32_bf16 v[28:31], v[156:159], v[188:191], v[28:31]
	v_mfma_f32_16x16x32_bf16 v[24:27], v[164:167], v[188:191], v[24:27]
	v_mfma_f32_16x16x32_bf16 v[24:27], v[160:163], v[184:187], v[24:27]
	v_mfma_f32_16x16x32_bf16 v[8:11], v[160:163], v[192:195], v[8:11]
	v_mfma_f32_16x16x32_bf16 v[8:11], v[164:167], v[196:199], v[8:11]
	v_mfma_f32_16x16x32_bf16 v[12:15], v[156:159], v[196:199], v[12:15]
	v_mfma_f32_16x16x32_bf16 v[12:15], v[152:155], v[192:195], v[12:15]
	s_setprio 0
	s_barrier
	s_add_u32 s42, s42, 0x40080
	s_addc_u32 s43, s43, 0
	s_add_i32 s44, s44, s51
	v_lshl_add_u64 v[144:145], s[42:43], 0, v[130:131]
	s_mov_b32 m0, s44
	s_nop 0
	global_load_lds_dwordx4 v[144:145], off
	v_lshl_add_u64 v[144:145], s[42:43], 0, v[134:135]
	s_add_i32 m0, s44, 0x2000
	s_nop 0
	global_load_lds_dwordx4 v[144:145], off
	s_waitcnt vmcnt(6)
	s_barrier
	s_setprio 1
	v_mfma_f32_16x16x32_bf16 v[52:55], v[200:203], v[168:171], v[52:55]
	v_mfma_f32_16x16x32_bf16 v[52:55], v[204:207], v[172:175], v[52:55]
	v_mfma_f32_16x16x32_bf16 v[48:51], v[214:217], v[172:175], v[48:51]
	v_mfma_f32_16x16x32_bf16 v[48:51], v[210:213], v[168:171], v[48:51]
	v_mfma_f32_16x16x32_bf16 v[32:35], v[210:213], v[176:179], v[32:35]
	v_mfma_f32_16x16x32_bf16 v[32:35], v[214:217], v[180:183], v[32:35]
	v_mfma_f32_16x16x32_bf16 v[36:39], v[204:207], v[180:183], v[36:39]
	v_mfma_f32_16x16x32_bf16 v[36:39], v[200:203], v[176:179], v[36:39]
	v_mfma_f32_16x16x32_bf16 v[20:23], v[200:203], v[184:187], v[20:23]
	v_mfma_f32_16x16x32_bf16 v[20:23], v[204:207], v[188:191], v[20:23]
	v_mfma_f32_16x16x32_bf16 v[16:19], v[214:217], v[188:191], v[16:19]
	v_mfma_f32_16x16x32_bf16 v[16:19], v[210:213], v[184:187], v[16:19]
	v_mfma_f32_16x16x32_bf16 v[0:3], v[210:213], v[192:195], v[0:3]
	v_mfma_f32_16x16x32_bf16 v[0:3], v[214:217], v[196:199], v[0:3]
	v_mfma_f32_16x16x32_bf16 v[4:7], v[204:207], v[196:199], v[4:7]
	v_mfma_f32_16x16x32_bf16 v[4:7], v[200:203], v[192:195], v[4:7]
	s_setprio 0
	s_add_i32 s70, s70, 2
	s_add_u32 s40, s40, 0x100
	s_addc_u32 s41, s41, 0
	s_add_u32 s23, s23, 0x100
	s_addc_u32 s25, s25, 0
	s_cmp_gt_u32 s70, 13
	s_barrier
	s_cbranch_scc0 .LBB0_433
	v_lshl_add_u32 v152, s38, 8, v146
	v_max_f32_e32 v120, 0, v120
	v_ashrrev_i32_e32 v153, 31, v152
	v_max_f32_e32 v121, 0, v121
	v_max_f32_e32 v122, 0, v122
	v_lshl_or_b32 v144, s69, 8, v148
	v_lshlrev_b64 v[154:155], 13, v[152:153]
	v_mul_f32_e32 v153, v120, v120
	v_max_f32_e32 v120, 0, v125
	v_ashrrev_i32_e32 v145, 31, v144
	v_max_f32_e32 v124, 0, v124
	v_mul_f32_e32 v125, v121, v121
	v_max_f32_e32 v121, 0, v126
	v_mul_f32_e32 v126, v122, v122
	v_max_f32_e32 v122, 0, v127
	v_max_f32_e32 v123, 0, v123
	v_lshl_add_u64 v[154:155], s[10:11], 0, v[154:155]
	v_lshlrev_b64 v[156:157], 1, v[144:145]
	v_mul_f32_e32 v120, v120, v120
	v_max_f32_e32 v112, 0, v112
	v_lshl_add_u64 v[144:145], v[154:155], 0, v[156:157]
	v_mul_f32_e32 v124, v124, v124
	v_mul_f32_e32 v121, v121, v121
	v_mul_f32_e32 v122, v122, v122
	v_mul_f32_e32 v123, v123, v123
	v_cvt_pk_bf16_f32 v120, v124, v120
	v_max_f32_e32 v113, 0, v113
	v_max_f32_e32 v114, 0, v114
	v_cvt_pk_bf16_f32 v121, v121, v122
	v_cvt_pk_bf16_f32 v122, v153, v125
	v_cvt_pk_bf16_f32 v123, v126, v123
	global_store_dwordx4 v[144:145], v[120:123], off
	s_nop 1
	v_mul_f32_e32 v120, v112, v112
	v_max_f32_e32 v112, 0, v117
	v_max_f32_e32 v116, 0, v116
	v_mul_f32_e32 v117, v113, v113
	v_max_f32_e32 v113, 0, v118
	v_mul_f32_e32 v118, v114, v114
	v_max_f32_e32 v114, 0, v119
	v_max_f32_e32 v115, 0, v115
	v_mul_f32_e32 v112, v112, v112
	v_mul_f32_e32 v116, v116, v116
	v_mul_f32_e32 v113, v113, v113
	v_mul_f32_e32 v114, v114, v114
	v_mul_f32_e32 v115, v115, v115
	v_cvt_pk_bf16_f32 v112, v116, v112
	v_max_f32_e32 v104, 0, v104
	v_cvt_pk_bf16_f32 v113, v113, v114
	v_cvt_pk_bf16_f32 v114, v120, v117
	v_cvt_pk_bf16_f32 v115, v118, v115
	global_store_dwordx4 v[144:145], v[112:115], off offset:256
	s_nop 0
	v_max_f32_e32 v105, 0, v105
	v_or_b32_e32 v112, 16, v152
	v_max_f32_e32 v106, 0, v106
	v_ashrrev_i32_e32 v113, 31, v112
	v_mul_f32_e32 v114, v104, v104
	v_max_f32_e32 v104, 0, v109
	v_lshlrev_b64 v[112:113], 13, v[112:113]
	v_max_f32_e32 v108, 0, v108
	v_mul_f32_e32 v109, v105, v105
	v_max_f32_e32 v105, 0, v110
	v_mul_f32_e32 v110, v106, v106
	v_max_f32_e32 v106, 0, v111
	v_max_f32_e32 v107, 0, v107
	v_lshl_add_u64 v[112:113], s[10:11], 0, v[112:113]
	v_mul_f32_e32 v104, v104, v104
	v_max_f32_e32 v96, 0, v96
	v_lshl_add_u64 v[112:113], v[112:113], 0, v[156:157]
	v_mul_f32_e32 v108, v108, v108
	v_mul_f32_e32 v105, v105, v105
	v_mul_f32_e32 v106, v106, v106
	v_mul_f32_e32 v107, v107, v107
	v_cvt_pk_bf16_f32 v104, v108, v104
	v_max_f32_e32 v97, 0, v97
	v_max_f32_e32 v98, 0, v98
	v_cvt_pk_bf16_f32 v105, v105, v106
	v_cvt_pk_bf16_f32 v106, v114, v109
	v_cvt_pk_bf16_f32 v107, v110, v107
	global_store_dwordx4 v[112:113], v[104:107], off
	s_nop 1
	v_mul_f32_e32 v104, v96, v96
	v_max_f32_e32 v96, 0, v101
	v_max_f32_e32 v100, 0, v100
; __device__ __forceinline__ unsigned cvt_pk_bf16(float lo, float hi) { unsigned r; asm volatile("v_cvt_pk_bf16_f32 %0, %1, %2" : "=v"(r) : "v"(lo), "v"(hi)); return r; }
;     __device__ __forceinline__ void operator()(const f32x4 (&acc)[2][2][4][2], const Unit& u, int ui, int wr, int wc, int fr, int fq) const {
;     ...
;         for (int ai = 0; ai < 2; ++ai)
; #pragma unroll
;             for (int m = 0; m < 4; ++m) { bf16_t* rowp = hid + (size_t)(row0 + ai * 128 + m * 16) * DFF + col0;
; #pragma unroll
;                 for (int bj = 0; bj < 2; ++bj) { f32x4 v0 = acc[ai][bj][m][0], v1 = acc[ai][bj][m][1];
; #pragma unroll
;                     for (int j = 0; j < 4; ++j) { const float a = fmaxf(v0[j], 0.f), b = fmaxf(v1[j], 0.f); v0[j] = a * a; v1[j] = b * b; }
;                     u32x4 w; w.x = cvt_pk_bf16(v0[0], v0[1]); w.y = cvt_pk_bf16(v0[2], v0[3]); w.z = cvt_pk_bf16(v1[0], v1[1]); w.w = cvt_pk_bf16(v1[2], v1[3]);
;                     *(u32x4*)(rowp + bj * 128) = w; } }
	v_mul_f32_e32 v101, v97, v97
	v_max_f32_e32 v97, 0, v102
	v_mul_f32_e32 v102, v98, v98
	v_max_f32_e32 v98, 0, v103
	v_max_f32_e32 v99, 0, v99
	v_mul_f32_e32 v96, v96, v96
	v_mul_f32_e32 v100, v100, v100
	v_mul_f32_e32 v97, v97, v97
	v_mul_f32_e32 v98, v98, v98
	v_mul_f32_e32 v99, v99, v99
	v_cvt_pk_bf16_f32 v96, v100, v96
	v_max_f32_e32 v88, 0, v88
	v_cvt_pk_bf16_f32 v97, v97, v98
	v_cvt_pk_bf16_f32 v98, v104, v101
	v_cvt_pk_bf16_f32 v99, v102, v99
	global_store_dwordx4 v[112:113], v[96:99], off offset:256
	s_nop 0
	v_max_f32_e32 v89, 0, v89
	v_or_b32_e32 v96, 32, v152
	v_max_f32_e32 v90, 0, v90
	v_ashrrev_i32_e32 v97, 31, v96
	v_mul_f32_e32 v98, v88, v88
	v_max_f32_e32 v88, 0, v93
	v_lshlrev_b64 v[96:97], 13, v[96:97]
	v_max_f32_e32 v92, 0, v92
	v_mul_f32_e32 v93, v89, v89
	v_max_f32_e32 v89, 0, v94
	v_mul_f32_e32 v94, v90, v90
	v_max_f32_e32 v90, 0, v95
	v_max_f32_e32 v91, 0, v91
	v_lshl_add_u64 v[96:97], s[10:11], 0, v[96:97]
	v_mul_f32_e32 v88, v88, v88
	v_max_f32_e32 v80, 0, v80
	v_lshl_add_u64 v[96:97], v[96:97], 0, v[156:157]
	v_mul_f32_e32 v92, v92, v92
	v_mul_f32_e32 v89, v89, v89
	v_mul_f32_e32 v90, v90, v90
	v_mul_f32_e32 v91, v91, v91
	v_cvt_pk_bf16_f32 v88, v92, v88
	v_max_f32_e32 v81, 0, v81
	v_max_f32_e32 v82, 0, v82
	v_cvt_pk_bf16_f32 v89, v89, v90
	v_cvt_pk_bf16_f32 v90, v98, v93
	v_cvt_pk_bf16_f32 v91, v94, v91
	global_store_dwordx4 v[96:97], v[88:91], off
	s_nop 1
	v_mul_f32_e32 v88, v80, v80
	v_max_f32_e32 v80, 0, v85
	v_max_f32_e32 v84, 0, v84
	v_mul_f32_e32 v85, v81, v81
	v_max_f32_e32 v81, 0, v86
	v_mul_f32_e32 v86, v82, v82
	v_max_f32_e32 v82, 0, v87
	v_max_f32_e32 v83, 0, v83
	v_mul_f32_e32 v80, v80, v80
	v_mul_f32_e32 v84, v84, v84
	v_mul_f32_e32 v81, v81, v81
	v_mul_f32_e32 v82, v82, v82
	v_mul_f32_e32 v83, v83, v83
	v_cvt_pk_bf16_f32 v80, v84, v80
	v_max_f32_e32 v72, 0, v72
	v_cvt_pk_bf16_f32 v81, v81, v82
	v_cvt_pk_bf16_f32 v82, v88, v85
	v_cvt_pk_bf16_f32 v83, v86, v83
	global_store_dwordx4 v[96:97], v[80:83], off offset:256
	s_nop 0
	v_max_f32_e32 v73, 0, v73
	v_or_b32_e32 v80, 48, v152
	v_max_f32_e32 v74, 0, v74
	v_ashrrev_i32_e32 v81, 31, v80
	v_mul_f32_e32 v82, v72, v72
	v_max_f32_e32 v72, 0, v77
	v_lshlrev_b64 v[80:81], 13, v[80:81]
	v_max_f32_e32 v76, 0, v76
	v_mul_f32_e32 v77, v73, v73
	v_max_f32_e32 v73, 0, v78
	v_mul_f32_e32 v78, v74, v74
	v_max_f32_e32 v74, 0, v79
	v_max_f32_e32 v75, 0, v75
	v_lshl_add_u64 v[80:81], s[10:11], 0, v[80:81]
	v_mul_f32_e32 v72, v72, v72
	v_max_f32_e32 v64, 0, v64
	v_max_f32_e32 v65, 0, v65
	v_max_f32_e32 v66, 0, v66
	v_lshl_add_u64 v[80:81], v[80:81], 0, v[156:157]
	v_mul_f32_e32 v76, v76, v76
	v_mul_f32_e32 v73, v73, v73
	v_mul_f32_e32 v74, v74, v74
	v_mul_f32_e32 v75, v75, v75
	v_cvt_pk_bf16_f32 v72, v76, v72
	v_cvt_pk_bf16_f32 v73, v73, v74
	v_cvt_pk_bf16_f32 v74, v82, v77
	v_cvt_pk_bf16_f32 v75, v78, v75
	global_store_dwordx4 v[80:81], v[72:75], off
	v_max_f32_e32 v68, 0, v68
	v_max_f32_e32 v67, 0, v67
	v_mul_f32_e32 v72, v64, v64
	v_max_f32_e32 v64, 0, v69
	v_mul_f32_e32 v69, v65, v65
	v_max_f32_e32 v65, 0, v70
	v_mul_f32_e32 v70, v66, v66
	v_max_f32_e32 v66, 0, v71
	v_mul_f32_e32 v64, v64, v64
	v_mul_f32_e32 v65, v65, v65
	v_mul_f32_e32 v66, v66, v66
	v_max_f32_e32 v56, 0, v56
	v_mul_f32_e32 v68, v68, v68
	v_mul_f32_e32 v67, v67, v67
	v_cvt_pk_bf16_f32 v64, v68, v64
	v_cvt_pk_bf16_f32 v65, v65, v66
	v_cvt_pk_bf16_f32 v66, v72, v69
	v_max_f32_e32 v57, 0, v57
	v_max_f32_e32 v58, 0, v58
	v_cvt_pk_bf16_f32 v67, v70, v67
	global_store_dwordx4 v[80:81], v[64:67], off offset:256
	s_nop 0
	v_max_f32_e32 v60, 0, v60
	v_mul_f32_e32 v66, v56, v56
	v_max_f32_e32 v56, 0, v61
	v_mul_f32_e32 v61, v57, v57
	v_max_f32_e32 v57, 0, v62
	v_mul_f32_e32 v62, v58, v58
	v_max_f32_e32 v58, 0, v63
	v_mul_f32_e32 v60, v60, v60
	v_mul_f32_e32 v56, v56, v56
	v_max_f32_e32 v59, 0, v59
	v_mul_f32_e32 v57, v57, v57
	v_mul_f32_e32 v58, v58, v58
	v_cvt_pk_bf16_f32 v56, v60, v56
	v_add_co_u32_e32 v60, vcc, s65, v144
	v_max_f32_e32 v48, 0, v48
	v_max_f32_e32 v49, 0, v49
	v_max_f32_e32 v50, 0, v50
	v_mul_f32_e32 v59, v59, v59
	v_cvt_pk_bf16_f32 v57, v57, v58
	v_cvt_pk_bf16_f32 v58, v66, v61
	v_addc_co_u32_e32 v61, vcc, 0, v145, vcc
	v_cvt_pk_bf16_f32 v59, v62, v59
	global_store_dwordx4 v[60:61], v[56:59], off
	v_max_f32_e32 v52, 0, v52
	v_max_f32_e32 v51, 0, v51
	v_mul_f32_e32 v56, v48, v48
	v_max_f32_e32 v48, 0, v53
	v_mul_f32_e32 v53, v49, v49
	v_max_f32_e32 v49, 0, v54
	v_mul_f32_e32 v54, v50, v50
	v_max_f32_e32 v50, 0, v55
	v_mul_f32_e32 v48, v48, v48
	v_mul_f32_e32 v49, v49, v49
	v_mul_f32_e32 v50, v50, v50
	v_max_f32_e32 v40, 0, v40
	v_lshl_add_u64 v[64:65], v[144:145], 0, s[14:15]
; __device__ __forceinline__ unsigned cvt_pk_bf16(float lo, float hi) { unsigned r; asm volatile("v_cvt_pk_bf16_f32 %0, %1, %2" : "=v"(r) : "v"(lo), "v"(hi)); return r; }
; #define PG8_WAIT_V(n) asm volatile("s_waitcnt vmcnt(" #n ")" ::: "memory")
; #define PG8_BAR __builtin_amdgcn_s_barrier()
; template <class Epi, class Ptrs>
; __device__ __forceinline__ void gemm_phase(LAS unsigned char* lds, const int K, const StaticOrder& S, const Ptrs& P, const Epi& E) {
;     ...
;         if (!has_next) break;
; #pragma unroll
;         for (int a = 0; a < 2; ++a)
; #pragma unroll
;             for (int b = 0; b < 2; ++b)
; #pragma unroll
;                 for (int m = 0; m < 4; ++m)
; #pragma unroll
;                     for (int n = 0; n < 2; ++n) acc[a][b][m][n] = (f32x4){0.f, 0.f, 0.f, 0.f};
;         cur = nxt; cA = nA; cB = nB; ++ui;
;     }
;     PG8_WAIT_V(0);
;     if (wr == 0) PG8_BAR;
;     PG8_BAR;
;     __device__ __forceinline__ void operator()(const f32x4 (&acc)[2][2][4][2], const Unit& u, int ui, int wr, int wc, int fr, int fq) const {
;     ...
;         for (int ai = 0; ai < 2; ++ai)
; #pragma unroll
;             for (int m = 0; m < 4; ++m) { bf16_t* rowp = hid + (size_t)(row0 + ai * 128 + m * 16) * DFF + col0;
; #pragma unroll
;                 for (int bj = 0; bj < 2; ++bj) { f32x4 v0 = acc[ai][bj][m][0], v1 = acc[ai][bj][m][1];
; #pragma unroll
;                     for (int j = 0; j < 4; ++j) { const float a = fmaxf(v0[j], 0.f), b = fmaxf(v1[j], 0.f); v0[j] = a * a; v1[j] = b * b; }
;                     u32x4 w; w.x = cvt_pk_bf16(v0[0], v0[1]); w.y = cvt_pk_bf16(v0[2], v0[3]); w.z = cvt_pk_bf16(v1[0], v1[1]); w.w = cvt_pk_bf16(v1[2], v1[3]);
;                     *(u32x4*)(rowp + bj * 128) = w; } }
	v_mul_f32_e32 v52, v52, v52
	v_mul_f32_e32 v51, v51, v51
	v_cvt_pk_bf16_f32 v48, v52, v48
	v_cvt_pk_bf16_f32 v49, v49, v50
	v_cvt_pk_bf16_f32 v50, v56, v53
	v_max_f32_e32 v41, 0, v41
	v_max_f32_e32 v42, 0, v42
	v_cvt_pk_bf16_f32 v51, v54, v51
	global_store_dwordx4 v[64:65], v[48:51], off offset:256
	s_nop 0
	v_max_f32_e32 v44, 0, v44
	v_mul_f32_e32 v50, v40, v40
	v_max_f32_e32 v40, 0, v45
	v_mul_f32_e32 v45, v41, v41
	v_max_f32_e32 v41, 0, v46
	v_mul_f32_e32 v46, v42, v42
	v_max_f32_e32 v42, 0, v47
	v_mul_f32_e32 v44, v44, v44
	v_mul_f32_e32 v40, v40, v40
	v_max_f32_e32 v43, 0, v43
	v_mul_f32_e32 v41, v41, v41
	v_mul_f32_e32 v42, v42, v42
	v_cvt_pk_bf16_f32 v40, v44, v40
	v_add_co_u32_e32 v44, vcc, s66, v144
	v_max_f32_e32 v32, 0, v32
	v_max_f32_e32 v33, 0, v33
	v_max_f32_e32 v34, 0, v34
	v_mul_f32_e32 v43, v43, v43
	v_cvt_pk_bf16_f32 v41, v41, v42
	v_cvt_pk_bf16_f32 v42, v50, v45
	v_addc_co_u32_e32 v45, vcc, 0, v145, vcc
	v_cvt_pk_bf16_f32 v43, v46, v43
	global_store_dwordx4 v[44:45], v[40:43], off
	v_max_f32_e32 v36, 0, v36
	v_max_f32_e32 v35, 0, v35
	v_mul_f32_e32 v40, v32, v32
	v_max_f32_e32 v32, 0, v37
	v_mul_f32_e32 v37, v33, v33
	v_max_f32_e32 v33, 0, v38
	v_mul_f32_e32 v38, v34, v34
	v_max_f32_e32 v34, 0, v39
	v_mul_f32_e32 v32, v32, v32
	v_mul_f32_e32 v33, v33, v33
	v_mul_f32_e32 v34, v34, v34
	v_max_f32_e32 v24, 0, v24
	v_lshl_add_u64 v[48:49], v[144:145], 0, s[16:17]
	v_mul_f32_e32 v36, v36, v36
	v_mul_f32_e32 v35, v35, v35
	v_cvt_pk_bf16_f32 v32, v36, v32
	v_cvt_pk_bf16_f32 v33, v33, v34
	v_cvt_pk_bf16_f32 v34, v40, v37
	v_max_f32_e32 v25, 0, v25
	v_max_f32_e32 v26, 0, v26
	v_cvt_pk_bf16_f32 v35, v38, v35
	global_store_dwordx4 v[48:49], v[32:35], off offset:256
	s_nop 0
	v_max_f32_e32 v28, 0, v28
	v_mul_f32_e32 v34, v24, v24
	v_max_f32_e32 v24, 0, v29
	v_mul_f32_e32 v29, v25, v25
	v_max_f32_e32 v25, 0, v30
	v_mul_f32_e32 v30, v26, v26
	v_max_f32_e32 v26, 0, v31
	v_mul_f32_e32 v28, v28, v28
	v_mul_f32_e32 v24, v24, v24
	v_max_f32_e32 v27, 0, v27
	v_mul_f32_e32 v25, v25, v25
	v_mul_f32_e32 v26, v26, v26
	v_cvt_pk_bf16_f32 v24, v28, v24
	v_add_co_u32_e32 v28, vcc, s67, v144
	v_max_f32_e32 v16, 0, v16
	v_max_f32_e32 v17, 0, v17
	v_max_f32_e32 v18, 0, v18
	v_mul_f32_e32 v27, v27, v27
	v_cvt_pk_bf16_f32 v25, v25, v26
	v_cvt_pk_bf16_f32 v26, v34, v29
	v_addc_co_u32_e32 v29, vcc, 0, v145, vcc
	v_cvt_pk_bf16_f32 v27, v30, v27
	global_store_dwordx4 v[28:29], v[24:27], off
	v_max_f32_e32 v20, 0, v20
	v_max_f32_e32 v19, 0, v19
	v_mul_f32_e32 v24, v16, v16
	v_max_f32_e32 v16, 0, v21
	v_mul_f32_e32 v21, v17, v17
	v_max_f32_e32 v17, 0, v22
	v_mul_f32_e32 v22, v18, v18
	v_max_f32_e32 v18, 0, v23
	v_mul_f32_e32 v16, v16, v16
	v_mul_f32_e32 v17, v17, v17
	v_mul_f32_e32 v18, v18, v18
	v_max_f32_e32 v8, 0, v8
	v_lshl_add_u64 v[32:33], v[144:145], 0, s[18:19]
	v_mul_f32_e32 v20, v20, v20
	v_mul_f32_e32 v19, v19, v19
	v_cvt_pk_bf16_f32 v16, v20, v16
	v_cvt_pk_bf16_f32 v17, v17, v18
	v_cvt_pk_bf16_f32 v18, v24, v21
	v_max_f32_e32 v9, 0, v9
	v_max_f32_e32 v10, 0, v10
	v_cvt_pk_bf16_f32 v19, v22, v19
	global_store_dwordx4 v[32:33], v[16:19], off offset:256
	s_nop 0
	v_max_f32_e32 v12, 0, v12
	v_mul_f32_e32 v18, v8, v8
	v_max_f32_e32 v8, 0, v13
	v_mul_f32_e32 v13, v9, v9
	v_max_f32_e32 v9, 0, v14
	v_mul_f32_e32 v14, v10, v10
	v_max_f32_e32 v10, 0, v15
	v_mul_f32_e32 v12, v12, v12
	v_mul_f32_e32 v8, v8, v8
	v_max_f32_e32 v11, 0, v11
	v_mul_f32_e32 v9, v9, v9
	v_mul_f32_e32 v10, v10, v10
	v_cvt_pk_bf16_f32 v8, v12, v8
	v_add_co_u32_e32 v12, vcc, s68, v144
	v_max_f32_e32 v0, 0, v0
	v_max_f32_e32 v1, 0, v1
	v_max_f32_e32 v2, 0, v2
	v_mul_f32_e32 v11, v11, v11
	v_cvt_pk_bf16_f32 v9, v9, v10
	v_cvt_pk_bf16_f32 v10, v18, v13
	v_addc_co_u32_e32 v13, vcc, 0, v145, vcc
	v_cvt_pk_bf16_f32 v11, v14, v11
	global_store_dwordx4 v[12:13], v[8:11], off
	v_max_f32_e32 v3, 0, v3
	v_max_f32_e32 v4, 0, v4
	v_mul_f32_e32 v8, v0, v0
	v_max_f32_e32 v0, 0, v5
	v_mul_f32_e32 v5, v1, v1
	v_max_f32_e32 v1, 0, v6
	v_mul_f32_e32 v6, v2, v2
	v_max_f32_e32 v2, 0, v7
	v_lshl_add_u64 v[16:17], v[144:145], 0, s[20:21]
	v_mul_f32_e32 v0, v0, v0
	v_mul_f32_e32 v1, v1, v1
	v_mul_f32_e32 v2, v2, v2
	v_mul_f32_e32 v3, v3, v3
	s_and_b64 vcc, exec, s[4:5]
	s_mov_b32 s69, s22
	s_mov_b32 s38, s24
	s_mov_b64 s[40:41], s[0:1]
	s_mov_b64 s[42:43], s[36:37]
	v_mul_f32_e32 v4, v4, v4
	v_cvt_pk_bf16_f32 v0, v4, v0
	v_cvt_pk_bf16_f32 v1, v1, v2
	v_cvt_pk_bf16_f32 v2, v8, v5
	v_cvt_pk_bf16_f32 v3, v6, v3
	global_store_dwordx4 v[16:17], v[0:3], off offset:256
	s_cbranch_vccz .LBB0_428
	s_waitcnt vmcnt(0)
	s_cmpk_gt_u32 s46, 0xff
	s_cbranch_scc1 .LBB0_437
	s_barrier

; __device__ __forceinline__ unsigned xb_ld(unsigned* p)              { return __hip_atomic_load(p, __ATOMIC_RELAXED, __HIP_MEMORY_SCOPE_AGENT); }
; __device__ __forceinline__ void xcd_barrier_complete(unsigned* bar, unsigned x, unsigned& nloc, unsigned& nx) {
;     const unsigned G = gridDim.x * gridDim.y * gridDim.z;
;     unsigned sum, cnt, mine, sp = 0u;
;     for (;;) {
;         sum = 0u; cnt = 0u; mine = 0u;
; #pragma unroll
;         for (unsigned j = 0; j < 16; ++j) { const unsigned c = xb_ld(&bar[XB_XCNT(j)]); sum += c; cnt += (c > 0u) ? 1u : 0u; mine = (j == x) ? c : mine; }
; __device__ __forceinline__ void xcd_barrier(const XcdBarrier& b) {
;     asm volatile("s_waitcnt vmcnt(0)" ::: "memory");
;     __syncthreads();
;     if (threadIdx.x == 0) {
;         unsigned* bar = b.bar;
;         __builtin_amdgcn_s_waitcnt(0);
;         unsigned nloc = b.st[0], nx = b.st[1];
;         if (nloc == 0u) { xcd_barrier_complete(bar, b.x, nloc, nx); b.st[0] = nloc; b.st[1] = nx; }
.LBB0_438:
	s_nop 0
	s_nop 0
	s_nop 0
	s_nop 0
	s_nop 0
	s_nop 0
	s_nop 0
	s_nop 0
	s_nop 0
	s_nop 0
	s_nop 0
	s_nop 0
	s_nop 0
	s_nop 0
	s_nop 0
	s_nop 0
	s_nop 0
	s_nop 0
	s_nop 0
	s_nop 0
	s_nop 0
	s_nop 0
	s_nop 0
	s_nop 0
	s_nop 0
	s_nop 0
	s_nop 0
	s_nop 0
	s_nop 0
	s_nop 0
	s_nop 0
	s_nop 0
	s_nop 0
	s_nop 0
	s_nop 0
	s_nop 0
	s_nop 0
	s_nop 0
	s_nop 0
	s_nop 0
	s_nop 0
	s_nop 0
	s_nop 0
	s_nop 0
	s_nop 0
	s_nop 0
	s_nop 0
	s_nop 0
	s_nop 0
	s_nop 0
	s_nop 0
	s_nop 0
	s_nop 0
	s_nop 0
	s_cmp_gt_i32 s31, 5
	s_cselect_b64 s[0:1], -1, 0
	s_and_b64 s[4:5], s[6:7], s[0:1]
	s_andn2_b64 vcc, exec, s[4:5]
	s_cbranch_vccnz .LBB0_488
	s_waitcnt vmcnt(0)
	s_waitcnt vmcnt(0) lgkmcnt(0)
	s_barrier
	s_and_saveexec_b64 s[4:5], s[8:9]
	s_cbranch_execz .LBB0_487
	s_add_i32 s6, 0, 0x25ff0
	v_mov_b32_e32 v0, s6
	s_waitcnt vmcnt(0) expcnt(0) lgkmcnt(0)
	ds_read_b32 v2, v0
	s_add_i32 s6, 0, 0x25ff4
	v_mov_b32_e32 v0, s6
	ds_read_b32 v0, v0
	s_waitcnt lgkmcnt(1)
	v_cmp_ne_u32_e32 vcc, 0, v2
	s_cbranch_vccnz .LBB0_455
	s_load_dwordx2 s[10:11], s[52:53], 0x4
	s_add_u32 s6, s28, 0x3e800200
	s_addc_u32 s7, s29, 0
	s_add_u32 s8, s28, 0x3e800400
	s_addc_u32 s9, s29, 0
	s_waitcnt lgkmcnt(0)
	s_mul_i32 s31, s10, s3
	s_add_u32 s10, s28, 0x3e800500
	s_mul_i32 s31, s31, s11
	s_addc_u32 s11, s29, 0
	s_add_u32 s12, s28, 0x3e800600
	s_addc_u32 s13, s29, 0
	s_add_u32 s14, s28, 0x3e800700
	s_addc_u32 s15, s29, 0
	s_add_u32 s16, s28, 0x3e800800
	s_addc_u32 s17, s29, 0
	s_add_u32 s18, s28, 0x3e800900
	s_addc_u32 s19, s29, 0
	s_add_u32 s20, s28, 0x3e800a00
	s_addc_u32 s21, s29, 0
	s_add_u32 s22, s28, 0x3e800b00
	s_addc_u32 s23, s29, 0
	s_add_u32 s24, s28, 0x3e800c00
	s_addc_u32 s25, s29, 0
	s_add_u32 s36, s28, 0x3e800d00
	s_addc_u32 s37, s29, 0
	s_add_u32 s38, s28, 0x3e800e00
	s_addc_u32 s39, s29, 0
	s_add_u32 s40, s28, 0x3e800f00
	s_addc_u32 s41, s29, 0
	s_add_u32 s42, s28, 0x3e801000
	s_addc_u32 s43, s29, 0
	s_add_u32 s44, s28, 0x3e801100
	s_addc_u32 s45, s29, 0
	s_add_u32 s46, s28, 0x3e801200
	s_addc_u32 s47, s29, 0
	s_add_u32 s48, s28, 0x3e801300
	s_addc_u32 s49, s29, 0
	s_mov_b32 s56, 1
	v_mov_b32_e32 v16, 0
	s_branch .LBB0_443
